# P1 small-gemm K-section: coalesced full-line loads + LDS transpose
# speedup vs baseline: 1.0099x; 1.0099x over previous
; #define HG_MFMA(a, b, c) __builtin_amdgcn_mfma_f32_32x32x16_bf16((a), (b), (c), 0, 0, 0)
;     __device__ __forceinline__ void small_pre(int row, int c0, int c1, SPre& sp) const { sp.ss = sumsq2[row]; sp.h0 = unpack4(*(const u32x2*)(HB + (size_t)row * DM + c0)); sp.h1 = unpack4(*(const u32x2*)(HB + (size_t)row * DM + c1)); }
; template <int K, class Epi>
; __device__ __forceinline__ void small_gemm(unsigned char* lds, const bf16_t* A, const bf16_t* Bt, int row0, int br0, int br1, const Epi& E) {
;     int tid = threadIdx.x; asm volatile("" : "+v"(tid));
;     const int w = __builtin_amdgcn_readfirstlane(tid >> 6), lane = tid & 63, r = lane & 31, hh = lane >> 5;
;     constexpr int ks = K >> 3, NS = ks >> 4, UNR = NS <= 8 ? NS : 11; const int k0 = w * ks + 8 * hh;
;     const bf16_t* ap = A + (size_t)(row0 + r) * K + k0; const bf16_t* b0p = Bt + (size_t)(br0 + r) * K + k0; const bf16_t* b1p = Bt + (size_t)(br1 + r) * K + k0;
;     typename Epi::SPre spre; const int srow = row0 + ((tid >> 3) & 31), sc4 = (tid & 7) * 4;
;     if (tid < 256) E.small_pre(srow, br0 + sc4, br1 + sc4, spre);
;     f32x16 acc0, acc1;
; #pragma unroll
;     for (int i = 0; i < 16; ++i) { acc0[i] = 0.f; acc1[i] = 0.f; }
; #pragma unroll UNR
;     for (int s = 0; s < NS; ++s) { const bf16x8 a = *(const bf16x8*)(ap + 16 * s), b0 = *(const bf16x8*)(b0p + 16 * s), b1 = *(const bf16x8*)(b1p + 16 * s);
;         acc0 = HG_MFMA(a, b0, acc0); acc1 = HG_MFMA(a, b1, acc1); }
;     float* part = (float*)lds + (size_t)w * (2 * 32 * SG_P);
.LBB0_245:
	s_or_b64 exec, exec, s[12:13]
	s_lshl_b32 s14, s16, 5
	s_add_i32 s4, s14, 0x4000
	v_and_b32_e32 v76, 31, v44
	v_bfe_u32 v77, v44, 5, 1
	s_ashr_i32 s5, s25, 6
	s_lshl_b32 s37, s5, 8
	s_lshl_b32 s36, s4, 11
	s_add_i32 s36, s36, s37
	s_add_u32 s38, s82, s36
	s_addc_u32 s39, s83, 0
	s_lshl_b32 s36, s17, 11
	s_add_i32 s36, s36, s37
	s_add_u32 s40, s64, s36
	s_addc_u32 s41, s65, 0
	s_lshl_b32 s36, s24, 11
	s_add_i32 s36, s36, s37
	s_add_u32 s42, s64, s36
	s_addc_u32 s43, s65, 0
	v_and_b32_e32 v60, 63, v44
	v_lshrrev_b32_e32 v61, 4, v60
	v_and_b32_e32 v62, 7, v60
	v_xor_b32_e32 v62, v62, v61
	v_lshrrev_b32_e32 v61, 3, v60
	v_lshlrev_b32_e32 v62, 4, v62
	v_lshl_or_b32 v64, v61, 11, v62
	v_xor_b32_e32 v65, 64, v64
	v_add_u32_e32 v65, 0x4000, v65
	v_add_u32_e32 v66, 0x8000, v64
	v_xor_b32_e32 v67, 64, v64
	v_add_u32_e32 v67, 0xc000, v67
	global_load_dwordx4 v[88:91], v64, s[38:39]
	global_load_dwordx4 v[92:95], v65, s[38:39]
	global_load_dwordx4 v[96:99], v66, s[38:39]
	global_load_dwordx4 v[100:103], v67, s[38:39]
	global_load_dwordx4 v[104:107], v64, s[40:41]
	global_load_dwordx4 v[108:111], v65, s[40:41]
	global_load_dwordx4 v[112:115], v66, s[40:41]
	global_load_dwordx4 v[116:119], v67, s[40:41]
	global_load_dwordx4 v[120:123], v64, s[42:43]
	global_load_dwordx4 v[124:127], v65, s[42:43]
	global_load_dwordx4 v[128:131], v66, s[42:43]
	global_load_dwordx4 v[132:135], v67, s[42:43]
	global_load_dwordx4 v[136:139], v64, s[38:39] offset:128
	global_load_dwordx4 v[140:143], v65, s[38:39] offset:128
	global_load_dwordx4 v[144:147], v66, s[38:39] offset:128
	global_load_dwordx4 v[148:151], v67, s[38:39] offset:128
	global_load_dwordx4 v[152:155], v64, s[40:41] offset:128
	global_load_dwordx4 v[156:159], v65, s[40:41] offset:128
	global_load_dwordx4 v[160:163], v66, s[40:41] offset:128
	global_load_dwordx4 v[164:167], v67, s[40:41] offset:128
	global_load_dwordx4 v[168:171], v64, s[42:43] offset:128
	global_load_dwordx4 v[172:175], v65, s[42:43] offset:128
	global_load_dwordx4 v[180:183], v66, s[42:43] offset:128
	global_load_dwordx4 v[184:187], v67, s[42:43] offset:128
	s_mul_i32 s46, s5, 0x3000
	v_lshl_add_u32 v68, v60, 4, s46
	v_lshl_add_u32 v69, v76, 7, s46
	v_bfe_u32 v63, v76, 1, 3
	v_or_b32_e32 v46, 0, v77
	v_xor_b32_e32 v46, v46, v63
	v_lshl_add_u32 v46, v46, 4, v69
	v_or_b32_e32 v47, 2, v77
	v_xor_b32_e32 v47, v47, v63
	v_lshl_add_u32 v47, v47, 4, v69
	v_or_b32_e32 v48, 4, v77
	v_xor_b32_e32 v48, v48, v63
	v_lshl_add_u32 v48, v48, 4, v69
	v_or_b32_e32 v49, 6, v77
	v_xor_b32_e32 v49, v49, v63
	v_lshl_add_u32 v49, v49, 4, v69
	s_mulk_i32 s5, 0x2400
	v_lshlrev_b32_e32 v40, 2, v76
	s_add_i32 s5, s5, 0
	v_mul_u32_u24_e32 v58, 0x90, v77
	v_lshlrev_b32_e32 v54, 2, v58
	v_add3_u32 v55, s5, v40, v54
	v_add3_u32 v40, s5, v54, v40
	v_add_u32_e32 v54, 0x1000, v40
	v_add_u32_e32 v56, 0x400, v55
	v_add_u32_e32 v57, 0x1400, v40
	v_add_u32_e32 v58, 0xc00, v55
	v_add_u32_e32 v59, 0x1e00, v40
	s_waitcnt vmcnt(12)
	ds_write_b128 v68, v[88:91]
	ds_write_b128 v68, v[92:95] offset:1024
	ds_write_b128 v68, v[96:99] offset:2048
	ds_write_b128 v68, v[100:103] offset:3072
	ds_write_b128 v68, v[104:107] offset:4096
	ds_write_b128 v68, v[108:111] offset:5120
	ds_write_b128 v68, v[112:115] offset:6144
	ds_write_b128 v68, v[116:119] offset:7168
	ds_write_b128 v68, v[120:123] offset:8192
	ds_write_b128 v68, v[124:127] offset:9216
	ds_write_b128 v68, v[128:131] offset:10240
	ds_write_b128 v68, v[132:135] offset:11264
	s_waitcnt lgkmcnt(0)
	ds_read_b128 v[192:195], v46
	ds_read_b128 v[212:215], v46 offset:4096
	ds_read_b128 v[228:231], v46 offset:8192
	ds_read_b128 v[196:199], v47
	ds_read_b128 v[216:219], v47 offset:4096
	ds_read_b128 v[232:235], v47 offset:8192
	ds_read_b128 v[200:203], v48
	ds_read_b128 v[220:223], v48 offset:4096
	ds_read_b128 v[236:239], v48 offset:8192
	ds_read_b128 v[208:211], v49
	ds_read_b128 v[224:227], v49 offset:4096
	ds_read_b128 v[240:243], v49 offset:8192
	s_waitcnt lgkmcnt(9)
	v_mfma_f32_32x32x16_bf16 v[0:15], v[192:195], v[212:215], 0
	v_mfma_f32_32x32x16_bf16 v[16:31], v[192:195], v[228:231], 0
	s_waitcnt lgkmcnt(6)
	v_mfma_f32_32x32x16_bf16 v[0:15], v[196:199], v[216:219], v[0:15]
	v_mfma_f32_32x32x16_bf16 v[16:31], v[196:199], v[232:235], v[16:31]
	s_waitcnt lgkmcnt(3)
	v_mfma_f32_32x32x16_bf16 v[0:15], v[200:203], v[220:223], v[0:15]
	v_mfma_f32_32x32x16_bf16 v[16:31], v[200:203], v[236:239], v[16:31]
	s_waitcnt lgkmcnt(0)
	v_mfma_f32_32x32x16_bf16 v[0:15], v[208:211], v[224:227], v[0:15]
	v_mfma_f32_32x32x16_bf16 v[16:31], v[208:211], v[240:243], v[16:31]
	s_waitcnt vmcnt(0)
	ds_write_b128 v68, v[136:139]
	ds_write_b128 v68, v[140:143] offset:1024
	ds_write_b128 v68, v[144:147] offset:2048
	ds_write_b128 v68, v[148:151] offset:3072
	ds_write_b128 v68, v[152:155] offset:4096
	ds_write_b128 v68, v[156:159] offset:5120
	ds_write_b128 v68, v[160:163] offset:6144
	ds_write_b128 v68, v[164:167] offset:7168
	ds_write_b128 v68, v[168:171] offset:8192
	ds_write_b128 v68, v[172:175] offset:9216
	ds_write_b128 v68, v[180:183] offset:10240
	ds_write_b128 v68, v[184:187] offset:11264
	s_waitcnt lgkmcnt(0)
	ds_read_b128 v[192:195], v46
	ds_read_b128 v[212:215], v46 offset:4096
	ds_read_b128 v[228:231], v46 offset:8192
	ds_read_b128 v[196:199], v47
	ds_read_b128 v[216:219], v47 offset:4096
	ds_read_b128 v[232:235], v47 offset:8192
	ds_read_b128 v[200:203], v48
	ds_read_b128 v[220:223], v48 offset:4096
	ds_read_b128 v[236:239], v48 offset:8192
	ds_read_b128 v[208:211], v49
	ds_read_b128 v[224:227], v49 offset:4096
	ds_read_b128 v[240:243], v49 offset:8192
	s_waitcnt lgkmcnt(9)
	v_mfma_f32_32x32x16_bf16 v[0:15], v[192:195], v[212:215], v[0:15]
	v_mfma_f32_32x32x16_bf16 v[16:31], v[192:195], v[228:231], v[16:31]
	s_waitcnt lgkmcnt(6)
	v_mfma_f32_32x32x16_bf16 v[0:15], v[196:199], v[216:219], v[0:15]
	v_mfma_f32_32x32x16_bf16 v[16:31], v[196:199], v[232:235], v[16:31]
	s_waitcnt lgkmcnt(3)
	v_mfma_f32_32x32x16_bf16 v[0:15], v[200:203], v[220:223], v[0:15]
	v_mfma_f32_32x32x16_bf16 v[16:31], v[200:203], v[236:239], v[16:31]
	s_waitcnt lgkmcnt(0)
	v_mfma_f32_32x32x16_bf16 v[0:15], v[208:211], v[224:227], v[0:15]
	v_add_u32_e32 v50, 0x1600, v40
	v_add_u32_e32 v51, 0x800, v55
	v_add_u32_e32 v52, 0x1800, v40
	v_add_u32_e32 v53, 0x1c00, v40
	v_add_u32_e32 v40, 0x2000, v40
	v_mfma_f32_32x32x16_bf16 v[16:31], v[208:211], v[240:243], v[16:31]
	s_barrier
; __device__ __forceinline__ unsigned cvt_pk_bf16(float lo, float hi) { unsigned r; asm volatile("v_cvt_pk_bf16_f32 %0, %1, %2" : "=v"(r) : "v"(lo), "v"(hi)); return r; }
; __device__ __forceinline__ float sigmoidf_(float x) { return frcp(1.0f + __expf(-x)); }
; #define LDS_BARRIER() do { asm volatile("s_waitcnt lgkmcnt(0)" ::: "memory"); __builtin_amdgcn_s_barrier(); asm volatile("" ::: "memory"); } while (0)
; template <int K, class Epi>
; __device__ __forceinline__ void small_gemm(unsigned char* lds, const bf16_t* A, const bf16_t* Bt, int row0, int br0, int br1, const Epi& E) {
;     ...
;     float* part = (float*)lds + (size_t)w * (2 * 32 * SG_P);
; #pragma unroll
;     for (int g = 0; g < 4; ++g)
; #pragma unroll
;         for (int i = 0; i < 4; ++i) { part[(8 * g + 4 * hh + i) * SG_P + r] = acc0[4 * g + i]; part[(32 + 8 * g + 4 * hh + i) * SG_P + r] = acc1[4 * g + i]; }
;     LDS_BARRIER();
;     if (tid < 256) { const int row = tid >> 3, c4 = (tid & 7) * 4; f32x4 v0 = {0.f, 0.f, 0.f, 0.f}, v1 = {0.f, 0.f, 0.f, 0.f};
; #pragma unroll
;         for (int ww = 0; ww < 8; ++ww) { const float* pp = (const float*)lds + (size_t)ww * (2 * 32 * SG_P); v0 += *(const f32x4*)(pp + row * SG_P + c4); v1 += *(const f32x4*)(pp + (32 + row) * SG_P + c4); }
;         E.small(row0 + row, br0 + c4, br1 + c4, v0, v1, spre); }
;     __device__ __forceinline__ void small(int row, int c0p, int c1p, const f32x4& v0, const f32x4& v1, const SPre& sp) const {
;     ...
;         } else { const int n1 = c0 - 2048, cu = (n1 >> 8) * 128 + (n1 & 127); f32x4 uu;
; #pragma unroll
;             for (int j = 0; j < 4; ++j) uu[j] = v0[j] * sigmoidf_(v1[j]);
;             u32x2 w; w.x = cvt_pk_bf16(uu[0], uu[1]); w.y = cvt_pk_bf16(uu[2], uu[3]); *(u32x2*)(U + (size_t)row * 512 + cu) = w;
;             const int rs = row - MP; __builtin_nontemporal_store(uu, (f32x4*)(scs + ((size_t)((rs >> 2) * (CW - 1) + (CW - 1 - DS) + (rs & 3))) * MIXB + cu)); }
	s_nop 5
	ds_write2_b32 v55, v0, v1 offset1:36
	s_nop 4
	ds_write2_b32 v54, v16, v17 offset0:128 offset1:164
	ds_write2_b32 v55, v2, v3 offset0:72 offset1:108
	ds_write2_b32 v54, v18, v19 offset0:200 offset1:236
	ds_write2_b32 v56, v4, v5 offset0:32 offset1:68
	ds_write2_b32 v57, v20, v21 offset0:160 offset1:196
	ds_write2_b32 v56, v6, v7 offset0:104 offset1:140
	ds_write2_b32 v50, v22, v23 offset0:104 offset1:140
	ds_write2_b32 v51, v8, v9 offset0:64 offset1:100
	ds_write2_b32 v52, v24, v25 offset0:192 offset1:228
	ds_write2_b32 v51, v10, v11 offset0:136 offset1:172
	ds_write2_b32 v53, v26, v27 offset0:8 offset1:44
	ds_write2_b32 v58, v12, v13 offset0:96 offset1:132
	ds_write2_b32 v59, v28, v29 offset0:96 offset1:132
	ds_write2_b32 v58, v14, v15 offset0:168 offset1:204
	ds_write2_b32 v40, v30, v31 offset0:40 offset1:76
	s_waitcnt lgkmcnt(0)
	s_barrier
	s_and_saveexec_b64 s[12:13], vcc
	s_cbranch_execz .LBB0_236
	v_ashrrev_i32_e32 v10, 3, v44
	v_mul_lo_u32 v0, v10, s20
	v_lshlrev_b32_e32 v1, 2, v42
	v_add3_u32 v11, 0, v0, v1
	ds_read_b128 v[0:3], v11
	ds_read_b128 v[4:7], v11 offset:4608
	ds_read_b128 v[12:15], v11 offset:9216
	ds_read_b128 v[16:19], v11 offset:64512
	s_waitcnt lgkmcnt(0)
	v_pk_add_f32 v[8:9], v[2:3], 0 op_sel_hi:[1,0]
	v_pk_add_f32 v[20:21], v[0:1], 0 op_sel_hi:[1,0]
	ds_read_b128 v[0:3], v11 offset:13824
	v_pk_add_f32 v[22:23], v[6:7], 0 op_sel_hi:[1,0]
	v_pk_add_f32 v[24:25], v[4:5], 0 op_sel_hi:[1,0]
	ds_read_b128 v[4:7], v11 offset:18432
	v_pk_add_f32 v[8:9], v[8:9], v[14:15]
	v_pk_add_f32 v[20:21], v[20:21], v[12:13]
	s_waitcnt lgkmcnt(1)
	v_pk_add_f32 v[22:23], v[22:23], v[2:3]
	ds_read_b128 v[12:15], v11 offset:23040
	v_pk_add_f32 v[24:25], v[24:25], v[0:1]
	ds_read_b128 v[0:3], v11 offset:27648
	s_waitcnt lgkmcnt(2)
	v_pk_add_f32 v[6:7], v[8:9], v[6:7]
	v_pk_add_f32 v[8:9], v[20:21], v[4:5]
	s_waitcnt lgkmcnt(1)
	v_pk_add_f32 v[20:21], v[22:23], v[14:15]
	v_pk_add_f32 v[24:25], v[24:25], v[12:13]
	s_waitcnt lgkmcnt(0)
	v_pk_add_f32 v[26:27], v[6:7], v[2:3]
	ds_read_b128 v[2:5], v11 offset:32256
	v_pk_add_f32 v[28:29], v[8:9], v[0:1]
	ds_read_b128 v[6:9], v11 offset:36864
	v_add_u32_e32 v0, 0xfc00, v11
	ds_read_b128 v[12:15], v0 offset:4608
	s_waitcnt lgkmcnt(2)
	v_pk_add_f32 v[4:5], v[20:21], v[4:5]
	ds_read_b128 v[20:23], v11 offset:41472
	v_pk_add_f32 v[24:25], v[24:25], v[2:3]
	ds_read_b128 v[0:3], v11 offset:46080
	s_waitcnt lgkmcnt(3)
	v_pk_add_f32 v[8:9], v[26:27], v[8:9]
	v_pk_add_f32 v[26:27], v[28:29], v[6:7]
	s_waitcnt lgkmcnt(1)
	v_pk_add_f32 v[28:29], v[4:5], v[22:23]
	ds_read_b128 v[4:7], v11 offset:50688
	s_waitcnt lgkmcnt(1)
	v_pk_add_f32 v[8:9], v[8:9], v[2:3]
	v_pk_add_f32 v[26:27], v[26:27], v[0:1]
	ds_read_b128 v[0:3], v11 offset:59904
	v_pk_add_f32 v[24:25], v[24:25], v[20:21]
	ds_read_b128 v[20:23], v11 offset:55296
	s_waitcnt lgkmcnt(2)
	v_pk_add_f32 v[6:7], v[28:29], v[6:7]
	v_pk_add_f32 v[4:5], v[24:25], v[4:5]
	s_waitcnt lgkmcnt(1)
	v_pk_add_f32 v[2:3], v[6:7], v[2:3]
	v_pk_add_f32 v[4:5], v[4:5], v[0:1]
	v_pk_add_f32 v[0:1], v[2:3], v[14:15]
	v_pk_add_f32 v[2:3], v[4:5], v[12:13]
	v_and_b32_e32 v5, 0x7c, v45
	v_lshrrev_b64 v[12:13], v5, s[6:7]
	v_lshlrev_b32_e32 v11, 8, v12
	s_waitcnt lgkmcnt(0)
	v_pk_add_f32 v[8:9], v[8:9], v[22:23]
	v_pk_add_f32 v[20:21], v[26:27], v[20:21]
	v_add_u32_e32 v4, s4, v10
	v_and_b32_e32 v12, 0xf00, v11
	v_pk_add_f32 v[6:7], v[8:9], v[18:19]
	v_pk_add_f32 v[8:9], v[20:21], v[16:17]
	v_cmp_lt_u32_e32 vcc, s21, v12
	v_ashrrev_i32_e32 v5, 31, v4
	s_and_saveexec_b64 s[4:5], vcc
	s_xor_b64 s[4:5], exec, s[4:5]
	s_cbranch_execz .LBB0_248
	v_mul_f32_e32 v0, 0xbfb8aa3b, v0
	v_mul_f32_e32 v2, 0xbfb8aa3b, v2
	v_mul_f32_e32 v3, 0xbfb8aa3b, v3
	v_exp_f32_e32 v0, v0
	v_mul_f32_e32 v1, 0xbfb8aa3b, v1
	v_exp_f32_e32 v2, v2
	v_exp_f32_e32 v3, v3
	v_exp_f32_e32 v1, v1
	v_add_f32_e32 v0, 1.0, v0
	v_add_f32_e32 v2, 1.0, v2
	v_add_f32_e32 v3, 1.0, v3
	v_rcp_f32_e32 v14, v0
	v_add_f32_e32 v0, 1.0, v1
	v_rcp_f32_e32 v2, v2
	v_rcp_f32_e32 v3, v3
	v_rcp_f32_e32 v15, v0
	v_add_u32_e32 v11, 0xfffff800, v12
	v_readlane_b32 s16, v247, 36
	v_pk_mul_f32 v[0:1], v[8:9], v[2:3]
	v_pk_mul_f32 v[2:3], v[6:7], v[14:15]
	v_lshrrev_b32_e32 v6, 1, v11
	v_and_or_b32 v40, v43, s22, v6
	v_lshlrev_b64 v[4:5], 10, v[4:5]
	v_readlane_b32 s17, v247, 37
	v_lshlrev_b32_e32 v8, 1, v40
	v_mov_b32_e32 v9, v41
	v_lshl_add_u64 v[4:5], s[16:17], 0, v[4:5]
	v_lshl_add_u64 v[4:5], v[4:5], 0, v[8:9]
	v_cvt_pk_bf16_f32 v6, v0, v1
	v_cvt_pk_bf16_f32 v7, v2, v3
	global_store_dwordx2 v[4:5], v[6:7], off
	v_add_u32_e32 v4, s14, v10
	v_ashrrev_i32_e32 v4, 2, v4
	v_mul_lo_u32 v4, v4, 30
	v_bfe_u32 v5, v44, 3, 2
	v_add3_u32 v4, v5, v4, 26
	v_ashrrev_i32_e32 v5, 31, v4
	v_lshlrev_b64 v[4:5], 11, v[4:5]
	v_lshl_add_u64 v[4:5], s[8:9], 0, v[4:5]
	v_lshl_add_u64 v[4:5], v[40:41], 2, v[4:5]
	global_store_dwordx4 v[4:5], v[0:3], off nt
